# v18 + P0: waves of workgroups 0..15 convert 7 rows, waves of workgroups 144..159 convert 9 (the moved row)
# speedup vs baseline: 1.0094x; 1.0010x over previous
; __device__ __forceinline__ unsigned pk2(float lo, float hi) { const f32x2c_t v = {lo, hi}; return __builtin_bit_cast(unsigned, __builtin_convertvector(v, bf16x2c_t)); }
; __device__ __forceinline__ void phase_prep(const Params& p, LAS unsigned char* lds) {
;     ...
;         for (int row = gw; row < NTOK; row += NGW) {
;             const f32x4* xr = (const f32x4*)(p.x + (size_t)row * DM) + lane;
;             f32x4 v[4]; float s = 0.f;
; #pragma unroll
;             for (int j = 0; j < 4; ++j) { v[j] = __builtin_nontemporal_load(xr + 64 * j); s += (v[j][0] * v[j][0] + v[j][1] * v[j][1]) + (v[j][2] * v[j][2] + v[j][3] * v[j][3]); }
;             s = wave_sum(s);
;             if (lane == 0) RS[row] = 1.0f / sqrtf(s * (1.f / DM) + 1e-6f);
;             u32x2* o = (u32x2*)(XB + (size_t)row * DM) + lane;
; #pragma unroll
;             for (int j = 0; j < 4; ++j) __builtin_nontemporal_store((u32x2){pk2(v[j][0], v[j][1]), pk2(v[j][2], v[j][3])}, o + 64 * j);
;         }
.LBB0_47:
	v_add_u32_e32 v18, s0, v28
	s_movk_i32 s1, 0x4000
	v_cmp_gt_i32_e32 vcc, s1, v18
	v_mbcnt_lo_u32_b32 v250, -1, 0
	s_and_saveexec_b64 s[8:9], vcc
	s_cbranch_execz .LBB0_52
	v_mbcnt_hi_u32_b32 v2, -1, v250
	v_and_b32_e32 v1, 64, v2
	v_add_u32_e32 v3, 64, v1
	v_xor_b32_e32 v1, 1, v2
	v_cmp_lt_i32_e32 vcc, v1, v3
	v_xor_b32_e32 v4, 2, v2
	v_readlane_b32 s10, v255, 0
	v_cndmask_b32_e32 v1, v2, v1, vcc
	v_cmp_lt_i32_e32 vcc, v4, v3
	v_ashrrev_i32_e32 v19, 31, v18
	v_readlane_b32 s11, v255, 1
	v_cndmask_b32_e32 v4, v2, v4, vcc
	v_lshlrev_b32_e32 v29, 2, v4
	v_xor_b32_e32 v4, 4, v2
	v_cmp_lt_i32_e32 vcc, v4, v3
	s_mov_b64 s[6:7], 0x3310000
	v_lshlrev_b32_e32 v1, 2, v1
	v_cndmask_b32_e32 v4, v2, v4, vcc
	v_lshlrev_b32_e32 v30, 2, v4
	v_xor_b32_e32 v4, 8, v2
	v_cmp_lt_i32_e32 vcc, v4, v3
	v_cmp_eq_u32_e64 s[4:5], 0, v163
	v_add_u32_e32 v34, 0xfffff800, v18
	v_cndmask_b32_e32 v4, v2, v4, vcc
	v_lshlrev_b32_e32 v31, 2, v4
	v_xor_b32_e32 v4, 16, v2
	v_cmp_lt_i32_e32 vcc, v4, v3
	s_mov_b32 s1, 0xf800000
	v_mov_b32_e32 v35, 0x260
	v_cndmask_b32_e32 v4, v2, v4, vcc
	v_lshlrev_b32_e32 v32, 2, v4
	v_xor_b32_e32 v4, 32, v2
	v_cmp_lt_i32_e32 vcc, v4, v3
	s_mov_b64 s[14:15], 0x2000
	s_mov_b64 s[16:17], 0x400000
	v_cndmask_b32_e32 v2, v2, v4, vcc
	v_lshlrev_b32_e32 v33, 2, v2
	v_lshl_add_u64 v[2:3], v[18:19], 2, s[10:11]
	v_lshl_add_u64 v[20:21], v[2:3], 0, s[6:7]
	v_lshlrev_b64 v[2:3], 11, v[18:19]
	v_lshl_or_b32 v2, v163, 3, v2
	v_lshl_add_u64 v[2:3], s[10:11], 0, v[2:3]
	s_mov_b64 s[6:7], 0x400
	v_lshl_add_u64 v[22:23], v[2:3], 0, s[6:7]
	v_lshlrev_b64 v[2:3], 12, v[18:19]
	v_lshl_or_b32 v2, v163, 4, v2
	v_lshl_add_u64 v[2:3], s[76:77], 0, v[2:3]
	s_mov_b64 s[6:7], 0xc00
	v_lshl_add_u64 v[24:25], v[2:3], 0, s[6:7]
	s_mov_b64 s[10:11], 0
	v_mov_b32_e32 v19, 0x358637bd
	s_mov_b64 s[18:19], 0x800000
	s_movk_i32 s3, 0x37ff
	v_readfirstlane_b32 s98, v18
	s_sub_i32 s99, s98, 0x480
	s_cmp_lt_u32 s99, 0x80
	s_cselect_b32 s99, 1, 0
	s_cmp_lt_u32 s98, 0x80
	s_cbranch_scc0 .Lconv_b8
	s_movk_i32 s3, 0x2fff
.Lconv_b8:
	s_branch .LBB0_50
.LBB0_49:
	s_or_b64 exec, exec, s[20:21]
	v_cvt_pk_bf16_f32 v2, v2, v3
	v_cvt_pk_bf16_f32 v3, v4, v5
	global_store_dwordx2 v[22:23], v[2:3], off offset:-1024 nt
	v_cvt_pk_bf16_f32 v2, v6, v7
	v_cvt_pk_bf16_f32 v3, v8, v9
	global_store_dwordx2 v[22:23], v[2:3], off offset:-512 nt
	v_cvt_pk_bf16_f32 v2, v10, v11
	v_cvt_pk_bf16_f32 v3, v12, v13
	v_add_u32_e32 v34, 0x800, v34
	global_store_dwordx2 v[22:23], v[2:3], off nt
	v_cvt_pk_bf16_f32 v2, v14, v15
	v_cvt_pk_bf16_f32 v3, v16, v17
	v_cmp_lt_i32_e32 vcc, s3, v34
	global_store_dwordx2 v[22:23], v[2:3], off offset:512 nt
	v_lshl_add_u64 v[20:21], v[20:21], 0, s[14:15]
	v_lshl_add_u64 v[22:23], v[22:23], 0, s[16:17]
	v_lshl_add_u64 v[24:25], v[24:25], 0, s[18:19]
	s_cmp_eq_u32 s99, 1
	s_cbranch_scc0 .Lconv_std
	s_cbranch_vccz .Lconv_std
	s_mov_b32 s99, 0
	v_mov_b32_e32 v34, 0x3000
	s_mov_b32 s100, 0xffffce00
	s_mov_b32 s101, -1
	v_lshl_add_u64 v[20:21], v[20:21], 0, s[100:101]
	s_mov_b32 s100, 0xff9c0000
	v_lshl_add_u64 v[22:23], v[22:23], 0, s[100:101]
	s_mov_b32 s100, 0xff380000
	v_lshl_add_u64 v[24:25], v[24:25], 0, s[100:101]
	s_branch .LBB0_50
.Lconv_std:
	s_or_b64 s[10:11], vcc, s[10:11]
	s_andn2_b64 exec, exec, s[10:11]
	s_cbranch_execz .LBB0_52
